# last layer: the bf16 copy of x written by the final row pass (next layer's input, never read) is not stored
# baseline (speedup 1.0000x reference)
; DI u32x4 cvt8(f32x4 a, f32x4 b) { u32x4 o; o[0] = pack2(a[0], a[1]); o[1] = pack2(a[2], a[3]); o[2] = pack2(b[0], b[1]); o[3] = pack2(b[2], b[3]); return o; }
; DI void gemm_rownorm_residual(const Ctx& c, int m0, const bf16* A, int lda, int K, const bf16* Wt, const float* gpost,
;                               const float* xres, float* xdst, bf16* xbdst, bf16* lds, float* rowss, float* rstd_next) {
;     ...
;   __syncthreads();
;   {
;     const int row = tid >> 2, part = tid & 3;
;     const float rs = rsqrtf(((rowss[row] + rowss[128 + row]) + (rowss[256 + row] + rowss[384 + row])) * (1.0f / 1024.0f) + EPS);
;     float ss2 = 0.f;
;     for (int cc = part * 256; cc < part * 256 + 256; cc += 8) {
;       float y[8];
;       unpack8(*(const uint4*)(YS + (size_t)(m0 + row) * 1024 + cc), y);
;       const f32x4 x0 = *(const f32x4*)(xres + (size_t)(m0 + row) * DM + cc), x1 = *(const f32x4*)(xres + (size_t)(m0 + row) * DM + cc + 4);
;       const f32x4 g0 = *(const f32x4*)(gpost + cc), g1 = *(const f32x4*)(gpost + cc + 4);
;       f32x4 o0, o1;
; #pragma unroll
;       for (int e = 0; e < 4; ++e) { o0[e] = x0[e] + y[e] * rs * g0[e]; o1[e] = x1[e] + y[4 + e] * rs * g1[e]; ss2 += o0[e] * o0[e] + o1[e] * o1[e]; }
;       *(f32x4*)(xdst + (size_t)(m0 + row) * DM + cc) = o0; *(f32x4*)(xdst + (size_t)(m0 + row) * DM + cc + 4) = o1;
;       *(u32x4*)(xbdst + (size_t)(m0 + row) * DM + cc) = cvt8(o0, o1);
;     }
;     ss2 += __shfl_xor(ss2, 1); ss2 += __shfl_xor(ss2, 2);
;     if (part == 0) rstd_next[row] = rsqrtf(ss2 * (1.0f / 1024.0f) + EPS);
;   }
.LBB0_898:
	s_barrier
	v_readfirstlane_b32 s100, v186
	v_and_b32_e32 v0, 63, v186
	v_mov_b32_e32 v137, 0
	v_mov_b32_e32 v139, 0
	s_lshr_b32 s100, s100, 6
	s_lshl_b32 s100, s100, 4
	s_add_i32 s101, s18, s100
	v_lshlrev_b32_e32 v140, 4, v0
	v_lshlrev_b32_e32 v141, 3, v0
	v_xor_b32_e32 v27, 32, v0
	v_lshlrev_b32_e32 v27, 2, v27
	s_lshl_b32 s100, s100, 2
	s_add_i32 s100, s100, 0x24050
	v_mov_b32_e32 v26, s100
	s_lshl_b32 s101, s101, 11
	v_add_u32_e32 v136, s101, v141
	s_lshl_b32 s101, s101, 1
	v_add_u32_e32 v138, s101, v140
	v_readlane_b32 s0, v228, 52
	v_readlane_b32 s1, v228, 53
	s_nop 1
	v_lshl_add_u64 v[18:19], s[0:1], 0, v[136:137]
	v_readlane_b32 s0, v229, 58
	v_readlane_b32 s1, v229, 59
	s_nop 1
	v_lshl_add_u64 v[24:25], s[0:1], 0, v[136:137]
	v_readlane_b32 s0, v227, 48
	v_readlane_b32 s1, v227, 49
	s_nop 1
	v_lshl_add_u64 v[20:21], s[0:1], 0, v[138:139]
	v_readlane_b32 s0, v227, 48
	v_readlane_b32 s1, v227, 49
	s_nop 1
	v_lshl_add_u64 v[22:23], s[0:1], 0, v[138:139]
	v_readlane_b32 s101, v226, 17
	global_load_dwordx4 v[2:5], v140, s[8:9]
	global_load_dwordx4 v[6:9], v140, s[8:9] offset:1024
	global_load_dwordx4 v[10:13], v140, s[8:9] offset:2048
	global_load_dwordx4 v[14:17], v140, s[8:9] offset:3072
	s_mov_b32 s100, 0
	s_mov_b32 s0, 0x800
	s_mov_b32 s1, 0
	global_load_dwordx4 v[40:43], v[20:21], off
	global_load_dwordx4 v[44:47], v[20:21], off offset:1024
	global_load_dwordx4 v[48:51], v[20:21], off offset:2048
	global_load_dwordx4 v[52:55], v[20:21], off offset:3072
	global_load_dwordx2 v[104:105], v[18:19], off
	global_load_dwordx2 v[106:107], v[18:19], off offset:512
	global_load_dwordx2 v[108:109], v[18:19], off offset:1024
	global_load_dwordx2 v[110:111], v[18:19], off offset:1536
	v_lshl_add_u64 v[20:21], s[0:1], 1, v[20:21]
	v_lshl_add_u64 v[18:19], s[0:1], 0, v[18:19]
	global_load_dwordx4 v[56:59], v[20:21], off
	global_load_dwordx4 v[60:63], v[20:21], off offset:1024
	global_load_dwordx4 v[64:67], v[20:21], off offset:2048
	global_load_dwordx4 v[68:71], v[20:21], off offset:3072
	global_load_dwordx2 v[112:113], v[18:19], off
	global_load_dwordx2 v[114:115], v[18:19], off offset:512
	global_load_dwordx2 v[116:117], v[18:19], off offset:1024
	global_load_dwordx2 v[118:119], v[18:19], off offset:1536
	v_lshl_add_u64 v[20:21], s[0:1], 1, v[20:21]
	v_lshl_add_u64 v[18:19], s[0:1], 0, v[18:19]
	global_load_dwordx4 v[72:75], v[20:21], off
	global_load_dwordx4 v[76:79], v[20:21], off offset:1024
	global_load_dwordx4 v[80:83], v[20:21], off offset:2048
	global_load_dwordx4 v[84:87], v[20:21], off offset:3072
	global_load_dwordx2 v[120:121], v[18:19], off
	global_load_dwordx2 v[122:123], v[18:19], off offset:512
	global_load_dwordx2 v[124:125], v[18:19], off offset:1024
	global_load_dwordx2 v[126:127], v[18:19], off offset:1536
	v_lshl_add_u64 v[20:21], s[0:1], 1, v[20:21]
	v_lshl_add_u64 v[18:19], s[0:1], 0, v[18:19]
	global_load_dwordx4 v[88:91], v[20:21], off
	global_load_dwordx4 v[92:95], v[20:21], off offset:1024
	global_load_dwordx4 v[96:99], v[20:21], off offset:2048
	global_load_dwordx4 v[100:103], v[20:21], off offset:3072
	global_load_dwordx2 v[128:129], v[18:19], off
	global_load_dwordx2 v[130:131], v[18:19], off offset:512
	global_load_dwordx2 v[132:133], v[18:19], off offset:1024
	global_load_dwordx2 v[134:135], v[18:19], off offset:1536
	v_lshl_add_u64 v[20:21], s[0:1], 1, v[20:21]
	v_lshl_add_u64 v[18:19], s[0:1], 0, v[18:19]
.Lrp_d_loop:
	v_mov_b32_e32 v28, v26
	v_add_u32_e32 v29, 4, v26
	v_add_u32_e32 v30, 8, v26
	v_add_u32_e32 v31, 12, v26
	ds_read2st64_b32 v[136:137], v28 offset0:2 offset1:4
	ds_read2st64_b32 v[138:139], v28 offset0:6 offset1:8
	s_waitcnt lgkmcnt(0)
	v_add_f32_e32 v136, v136, v137
	v_add_f32_e32 v138, v138, v139
	v_mov_b32_e32 v36, 0
	v_add_f32_e32 v136, v136, v138
	s_nop 0
	v_fmamk_f32 v136, v136, 0x3a800000, v187
	s_nop 0
	v_rsq_f32_e32 v32, v136
	ds_read2st64_b32 v[136:137], v29 offset0:2 offset1:4
	ds_read2st64_b32 v[138:139], v29 offset0:6 offset1:8
	s_waitcnt lgkmcnt(0)
	v_add_f32_e32 v136, v136, v137
	v_add_f32_e32 v138, v138, v139
	v_mov_b32_e32 v37, 0
	v_add_f32_e32 v136, v136, v138
	s_nop 0
	v_fmamk_f32 v136, v136, 0x3a800000, v187
	s_nop 0
	v_rsq_f32_e32 v33, v136
	ds_read2st64_b32 v[136:137], v30 offset0:2 offset1:4
	ds_read2st64_b32 v[138:139], v30 offset0:6 offset1:8
	s_waitcnt lgkmcnt(0)
	v_add_f32_e32 v136, v136, v137
	v_add_f32_e32 v138, v138, v139
	v_mov_b32_e32 v38, 0
	v_add_f32_e32 v136, v136, v138
	s_nop 0
	v_fmamk_f32 v136, v136, 0x3a800000, v187
	s_nop 0
	v_rsq_f32_e32 v34, v136
	ds_read2st64_b32 v[136:137], v31 offset0:2 offset1:4
	ds_read2st64_b32 v[138:139], v31 offset0:6 offset1:8
	s_waitcnt lgkmcnt(0)
	v_add_f32_e32 v136, v136, v137
	v_add_f32_e32 v138, v138, v139
	v_mov_b32_e32 v39, 0
	v_add_f32_e32 v136, v136, v138
	s_nop 0
	v_fmamk_f32 v136, v136, 0x3a800000, v187
	s_nop 0
	v_rsq_f32_e32 v35, v136
	s_waitcnt vmcnt(0)
; DI u32x4 cvt8(f32x4 a, f32x4 b) { u32x4 o; o[0] = pack2(a[0], a[1]); o[1] = pack2(a[2], a[3]); o[2] = pack2(b[0], b[1]); o[3] = pack2(b[2], b[3]); return o; }
; DI void gemm_rownorm_residual(const Ctx& c, int m0, const bf16* A, int lda, int K, const bf16* Wt, const float* gpost,
;                               const float* xres, float* xdst, bf16* xbdst, bf16* lds, float* rowss, float* rstd_next) {
;     ...
;     for (int cc = part * 256; cc < part * 256 + 256; cc += 8) {
;       float y[8];
;       unpack8(*(const uint4*)(YS + (size_t)(m0 + row) * 1024 + cc), y);
;       const f32x4 x0 = *(const f32x4*)(xres + (size_t)(m0 + row) * DM + cc), x1 = *(const f32x4*)(xres + (size_t)(m0 + row) * DM + cc + 4);
;       const f32x4 g0 = *(const f32x4*)(gpost + cc), g1 = *(const f32x4*)(gpost + cc + 4);
;       f32x4 o0, o1;
; #pragma unroll
;       for (int e = 0; e < 4; ++e) { o0[e] = x0[e] + y[e] * rs * g0[e]; o1[e] = x1[e] + y[4 + e] * rs * g1[e]; ss2 += o0[e] * o0[e] + o1[e] * o1[e]; }
;       *(f32x4*)(xdst + (size_t)(m0 + row) * DM + cc) = o0; *(f32x4*)(xdst + (size_t)(m0 + row) * DM + cc + 4) = o1;
;       *(u32x4*)(xbdst + (size_t)(m0 + row) * DM + cc) = cvt8(o0, o1);
;     }
	v_lshlrev_b32_e32 v136, 16, v104
	v_and_b32_e32 v137, 0xffff0000, v104
	v_lshlrev_b32_e32 v138, 16, v105
	v_and_b32_e32 v139, 0xffff0000, v105
	v_mul_f32_e32 v136, v32, v136
	v_mul_f32_e32 v137, v32, v137
	v_mul_f32_e32 v138, v32, v138
	v_mul_f32_e32 v139, v32, v139
	v_fmac_f32_e32 v40, v136, v2
	v_fmac_f32_e32 v41, v137, v3
	v_fmac_f32_e32 v42, v138, v4
	v_fmac_f32_e32 v43, v139, v5
	v_fmac_f32_e32 v36, v40, v40
	v_fmac_f32_e32 v36, v41, v41
	v_fmac_f32_e32 v36, v42, v42
	v_fmac_f32_e32 v36, v43, v43
	v_cvt_pk_bf16_f32 v104, v40, v41
	v_cvt_pk_bf16_f32 v105, v42, v43
	v_lshlrev_b32_e32 v136, 16, v106
	v_and_b32_e32 v137, 0xffff0000, v106
	v_lshlrev_b32_e32 v138, 16, v107
	v_and_b32_e32 v139, 0xffff0000, v107
	v_mul_f32_e32 v136, v32, v136
	v_mul_f32_e32 v137, v32, v137
	v_mul_f32_e32 v138, v32, v138
	v_mul_f32_e32 v139, v32, v139
	v_fmac_f32_e32 v44, v136, v6
	v_fmac_f32_e32 v45, v137, v7
	v_fmac_f32_e32 v46, v138, v8
	v_fmac_f32_e32 v47, v139, v9
	v_fmac_f32_e32 v36, v44, v44
	v_fmac_f32_e32 v36, v45, v45
	v_fmac_f32_e32 v36, v46, v46
	v_fmac_f32_e32 v36, v47, v47
	v_cvt_pk_bf16_f32 v106, v44, v45
	v_cvt_pk_bf16_f32 v107, v46, v47
	v_lshlrev_b32_e32 v136, 16, v108
	v_and_b32_e32 v137, 0xffff0000, v108
	v_lshlrev_b32_e32 v138, 16, v109
	v_and_b32_e32 v139, 0xffff0000, v109
	v_mul_f32_e32 v136, v32, v136
	v_mul_f32_e32 v137, v32, v137
	v_mul_f32_e32 v138, v32, v138
	v_mul_f32_e32 v139, v32, v139
	v_fmac_f32_e32 v48, v136, v10
	v_fmac_f32_e32 v49, v137, v11
	v_fmac_f32_e32 v50, v138, v12
	v_fmac_f32_e32 v51, v139, v13
	v_fmac_f32_e32 v36, v48, v48
	v_fmac_f32_e32 v36, v49, v49
	v_fmac_f32_e32 v36, v50, v50
	v_fmac_f32_e32 v36, v51, v51
	v_cvt_pk_bf16_f32 v108, v48, v49
	v_cvt_pk_bf16_f32 v109, v50, v51
	v_lshlrev_b32_e32 v136, 16, v110
	v_and_b32_e32 v137, 0xffff0000, v110
	v_lshlrev_b32_e32 v138, 16, v111
	v_and_b32_e32 v139, 0xffff0000, v111
	v_mul_f32_e32 v136, v32, v136
	v_mul_f32_e32 v137, v32, v137
	v_mul_f32_e32 v138, v32, v138
	v_mul_f32_e32 v139, v32, v139
	v_fmac_f32_e32 v52, v136, v14
	v_fmac_f32_e32 v53, v137, v15
	v_fmac_f32_e32 v54, v138, v16
	v_fmac_f32_e32 v55, v139, v17
	v_fmac_f32_e32 v36, v52, v52
	v_fmac_f32_e32 v36, v53, v53
	v_fmac_f32_e32 v36, v54, v54
	v_fmac_f32_e32 v36, v55, v55
	v_cvt_pk_bf16_f32 v110, v52, v53
	v_cvt_pk_bf16_f32 v111, v54, v55
	v_lshlrev_b32_e32 v136, 16, v112
	v_and_b32_e32 v137, 0xffff0000, v112
	v_lshlrev_b32_e32 v138, 16, v113
	v_and_b32_e32 v139, 0xffff0000, v113
	v_mul_f32_e32 v136, v33, v136
	v_mul_f32_e32 v137, v33, v137
	v_mul_f32_e32 v138, v33, v138
	v_mul_f32_e32 v139, v33, v139
	v_fmac_f32_e32 v56, v136, v2
	v_fmac_f32_e32 v57, v137, v3
	v_fmac_f32_e32 v58, v138, v4
	v_fmac_f32_e32 v59, v139, v5
	v_fmac_f32_e32 v37, v56, v56
	v_fmac_f32_e32 v37, v57, v57
	v_fmac_f32_e32 v37, v58, v58
	v_fmac_f32_e32 v37, v59, v59
	v_cvt_pk_bf16_f32 v112, v56, v57
	v_cvt_pk_bf16_f32 v113, v58, v59
	v_lshlrev_b32_e32 v136, 16, v114
	v_and_b32_e32 v137, 0xffff0000, v114
	v_lshlrev_b32_e32 v138, 16, v115
	v_and_b32_e32 v139, 0xffff0000, v115
	v_mul_f32_e32 v136, v33, v136
	v_mul_f32_e32 v137, v33, v137
	v_mul_f32_e32 v138, v33, v138
	v_mul_f32_e32 v139, v33, v139
	v_fmac_f32_e32 v60, v136, v6
	v_fmac_f32_e32 v61, v137, v7
	v_fmac_f32_e32 v62, v138, v8
	v_fmac_f32_e32 v63, v139, v9
	v_fmac_f32_e32 v37, v60, v60
	v_fmac_f32_e32 v37, v61, v61
	v_fmac_f32_e32 v37, v62, v62
	v_fmac_f32_e32 v37, v63, v63
	v_cvt_pk_bf16_f32 v114, v60, v61
	v_cvt_pk_bf16_f32 v115, v62, v63
	v_lshlrev_b32_e32 v136, 16, v116
	v_and_b32_e32 v137, 0xffff0000, v116
	v_lshlrev_b32_e32 v138, 16, v117
	v_and_b32_e32 v139, 0xffff0000, v117
	v_mul_f32_e32 v136, v33, v136
	v_mul_f32_e32 v137, v33, v137
	v_mul_f32_e32 v138, v33, v138
	v_mul_f32_e32 v139, v33, v139
	v_fmac_f32_e32 v64, v136, v10
	v_fmac_f32_e32 v65, v137, v11
	v_fmac_f32_e32 v66, v138, v12
	v_fmac_f32_e32 v67, v139, v13
	v_fmac_f32_e32 v37, v64, v64
	v_fmac_f32_e32 v37, v65, v65
	v_fmac_f32_e32 v37, v66, v66
	v_fmac_f32_e32 v37, v67, v67
	v_cvt_pk_bf16_f32 v116, v64, v65
	v_cvt_pk_bf16_f32 v117, v66, v67
	v_lshlrev_b32_e32 v136, 16, v118
	v_and_b32_e32 v137, 0xffff0000, v118
	v_lshlrev_b32_e32 v138, 16, v119
	v_and_b32_e32 v139, 0xffff0000, v119
	v_mul_f32_e32 v136, v33, v136
	v_mul_f32_e32 v137, v33, v137
	v_mul_f32_e32 v138, v33, v138
	v_mul_f32_e32 v139, v33, v139
	v_fmac_f32_e32 v68, v136, v14
	v_fmac_f32_e32 v69, v137, v15
	v_fmac_f32_e32 v70, v138, v16
	v_fmac_f32_e32 v71, v139, v17
	v_fmac_f32_e32 v37, v68, v68
	v_fmac_f32_e32 v37, v69, v69
	v_fmac_f32_e32 v37, v70, v70
	v_fmac_f32_e32 v37, v71, v71
	v_cvt_pk_bf16_f32 v118, v68, v69
	v_cvt_pk_bf16_f32 v119, v70, v71
	v_lshlrev_b32_e32 v136, 16, v120
	v_and_b32_e32 v137, 0xffff0000, v120
	v_lshlrev_b32_e32 v138, 16, v121
	v_and_b32_e32 v139, 0xffff0000, v121
	v_mul_f32_e32 v136, v34, v136
	v_mul_f32_e32 v137, v34, v137
	v_mul_f32_e32 v138, v34, v138
	v_mul_f32_e32 v139, v34, v139
	v_fmac_f32_e32 v72, v136, v2
	v_fmac_f32_e32 v73, v137, v3
	v_fmac_f32_e32 v74, v138, v4
	v_fmac_f32_e32 v75, v139, v5
	v_fmac_f32_e32 v38, v72, v72
	v_fmac_f32_e32 v38, v73, v73
	v_fmac_f32_e32 v38, v74, v74
	v_fmac_f32_e32 v38, v75, v75
	v_cvt_pk_bf16_f32 v120, v72, v73
	v_cvt_pk_bf16_f32 v121, v74, v75
	v_lshlrev_b32_e32 v136, 16, v122
	v_and_b32_e32 v137, 0xffff0000, v122
	v_lshlrev_b32_e32 v138, 16, v123
	v_and_b32_e32 v139, 0xffff0000, v123
	v_mul_f32_e32 v136, v34, v136
	v_mul_f32_e32 v137, v34, v137
	v_mul_f32_e32 v138, v34, v138
	v_mul_f32_e32 v139, v34, v139
	v_fmac_f32_e32 v76, v136, v6
	v_fmac_f32_e32 v77, v137, v7
	v_fmac_f32_e32 v78, v138, v8
	v_fmac_f32_e32 v79, v139, v9
	v_fmac_f32_e32 v38, v76, v76
	v_fmac_f32_e32 v38, v77, v77
; DI u32x4 cvt8(f32x4 a, f32x4 b) { u32x4 o; o[0] = pack2(a[0], a[1]); o[1] = pack2(a[2], a[3]); o[2] = pack2(b[0], b[1]); o[3] = pack2(b[2], b[3]); return o; }
; DI void gemm_rownorm_residual(const Ctx& c, int m0, const bf16* A, int lda, int K, const bf16* Wt, const float* gpost,
;                               const float* xres, float* xdst, bf16* xbdst, bf16* lds, float* rowss, float* rstd_next) {
;     ...
;       for (int e = 0; e < 4; ++e) { o0[e] = x0[e] + y[e] * rs * g0[e]; o1[e] = x1[e] + y[4 + e] * rs * g1[e]; ss2 += o0[e] * o0[e] + o1[e] * o1[e]; }
;       *(f32x4*)(xdst + (size_t)(m0 + row) * DM + cc) = o0; *(f32x4*)(xdst + (size_t)(m0 + row) * DM + cc + 4) = o1;
;       *(u32x4*)(xbdst + (size_t)(m0 + row) * DM + cc) = cvt8(o0, o1);
	v_fmac_f32_e32 v38, v78, v78
	v_fmac_f32_e32 v38, v79, v79
	v_cvt_pk_bf16_f32 v122, v76, v77
	v_cvt_pk_bf16_f32 v123, v78, v79
	v_lshlrev_b32_e32 v136, 16, v124
	v_and_b32_e32 v137, 0xffff0000, v124
	v_lshlrev_b32_e32 v138, 16, v125
	v_and_b32_e32 v139, 0xffff0000, v125
	v_mul_f32_e32 v136, v34, v136
	v_mul_f32_e32 v137, v34, v137
	v_mul_f32_e32 v138, v34, v138
	v_mul_f32_e32 v139, v34, v139
	v_fmac_f32_e32 v80, v136, v10
	v_fmac_f32_e32 v81, v137, v11
	v_fmac_f32_e32 v82, v138, v12
	v_fmac_f32_e32 v83, v139, v13
	v_fmac_f32_e32 v38, v80, v80
	v_fmac_f32_e32 v38, v81, v81
	v_fmac_f32_e32 v38, v82, v82
	v_fmac_f32_e32 v38, v83, v83
	v_cvt_pk_bf16_f32 v124, v80, v81
	v_cvt_pk_bf16_f32 v125, v82, v83
	v_lshlrev_b32_e32 v136, 16, v126
	v_and_b32_e32 v137, 0xffff0000, v126
	v_lshlrev_b32_e32 v138, 16, v127
	v_and_b32_e32 v139, 0xffff0000, v127
	v_mul_f32_e32 v136, v34, v136
	v_mul_f32_e32 v137, v34, v137
	v_mul_f32_e32 v138, v34, v138
	v_mul_f32_e32 v139, v34, v139
	v_fmac_f32_e32 v84, v136, v14
	v_fmac_f32_e32 v85, v137, v15
	v_fmac_f32_e32 v86, v138, v16
	v_fmac_f32_e32 v87, v139, v17
	v_fmac_f32_e32 v38, v84, v84
	v_fmac_f32_e32 v38, v85, v85
	v_fmac_f32_e32 v38, v86, v86
	v_fmac_f32_e32 v38, v87, v87
	v_cvt_pk_bf16_f32 v126, v84, v85
	v_cvt_pk_bf16_f32 v127, v86, v87
	v_lshlrev_b32_e32 v136, 16, v128
	v_and_b32_e32 v137, 0xffff0000, v128
	v_lshlrev_b32_e32 v138, 16, v129
	v_and_b32_e32 v139, 0xffff0000, v129
	v_mul_f32_e32 v136, v35, v136
	v_mul_f32_e32 v137, v35, v137
	v_mul_f32_e32 v138, v35, v138
	v_mul_f32_e32 v139, v35, v139
	v_fmac_f32_e32 v88, v136, v2
	v_fmac_f32_e32 v89, v137, v3
	v_fmac_f32_e32 v90, v138, v4
	v_fmac_f32_e32 v91, v139, v5
	v_fmac_f32_e32 v39, v88, v88
	v_fmac_f32_e32 v39, v89, v89
	v_fmac_f32_e32 v39, v90, v90
	v_fmac_f32_e32 v39, v91, v91
	v_cvt_pk_bf16_f32 v128, v88, v89
	v_cvt_pk_bf16_f32 v129, v90, v91
	v_lshlrev_b32_e32 v136, 16, v130
	v_and_b32_e32 v137, 0xffff0000, v130
	v_lshlrev_b32_e32 v138, 16, v131
	v_and_b32_e32 v139, 0xffff0000, v131
	v_mul_f32_e32 v136, v35, v136
	v_mul_f32_e32 v137, v35, v137
	v_mul_f32_e32 v138, v35, v138
	v_mul_f32_e32 v139, v35, v139
	v_fmac_f32_e32 v92, v136, v6
	v_fmac_f32_e32 v93, v137, v7
	v_fmac_f32_e32 v94, v138, v8
	v_fmac_f32_e32 v95, v139, v9
	v_fmac_f32_e32 v39, v92, v92
	v_fmac_f32_e32 v39, v93, v93
	v_fmac_f32_e32 v39, v94, v94
	v_fmac_f32_e32 v39, v95, v95
	v_cvt_pk_bf16_f32 v130, v92, v93
	v_cvt_pk_bf16_f32 v131, v94, v95
	v_lshlrev_b32_e32 v136, 16, v132
	v_and_b32_e32 v137, 0xffff0000, v132
	v_lshlrev_b32_e32 v138, 16, v133
	v_and_b32_e32 v139, 0xffff0000, v133
	v_mul_f32_e32 v136, v35, v136
	v_mul_f32_e32 v137, v35, v137
	v_mul_f32_e32 v138, v35, v138
	v_mul_f32_e32 v139, v35, v139
	v_fmac_f32_e32 v96, v136, v10
	v_fmac_f32_e32 v97, v137, v11
	v_fmac_f32_e32 v98, v138, v12
	v_fmac_f32_e32 v99, v139, v13
	v_fmac_f32_e32 v39, v96, v96
	v_fmac_f32_e32 v39, v97, v97
	v_fmac_f32_e32 v39, v98, v98
	v_fmac_f32_e32 v39, v99, v99
	v_cvt_pk_bf16_f32 v132, v96, v97
	v_cvt_pk_bf16_f32 v133, v98, v99
	v_lshlrev_b32_e32 v136, 16, v134
	v_and_b32_e32 v137, 0xffff0000, v134
	v_lshlrev_b32_e32 v138, 16, v135
	v_and_b32_e32 v139, 0xffff0000, v135
	v_mul_f32_e32 v136, v35, v136
	v_mul_f32_e32 v137, v35, v137
	v_mul_f32_e32 v138, v35, v138
	v_mul_f32_e32 v139, v35, v139
	v_fmac_f32_e32 v100, v136, v14
	v_fmac_f32_e32 v101, v137, v15
	v_fmac_f32_e32 v102, v138, v16
	v_fmac_f32_e32 v103, v139, v17
	v_fmac_f32_e32 v39, v100, v100
	v_fmac_f32_e32 v39, v101, v101
	v_fmac_f32_e32 v39, v102, v102
	v_fmac_f32_e32 v39, v103, v103
	v_cvt_pk_bf16_f32 v134, v100, v101
	v_cvt_pk_bf16_f32 v135, v102, v103
	global_store_dwordx4 v[22:23], v[40:43], off
	global_store_dwordx4 v[22:23], v[44:47], off offset:1024
	global_store_dwordx4 v[22:23], v[48:51], off offset:2048
	global_store_dwordx4 v[22:23], v[52:55], off offset:3072
	s_cmp_lg_u32 s101, 0
	s_cbranch_scc1 .Lrp_d_nxb0
	global_store_dwordx2 v[24:25], v[104:105], off
	global_store_dwordx2 v[24:25], v[106:107], off offset:512
	global_store_dwordx2 v[24:25], v[108:109], off offset:1024
	global_store_dwordx2 v[24:25], v[110:111], off offset:1536
.Lrp_d_nxb0:
	v_lshl_add_u64 v[22:23], s[0:1], 1, v[22:23]
	v_lshl_add_u64 v[24:25], s[0:1], 0, v[24:25]
	global_store_dwordx4 v[22:23], v[56:59], off
	global_store_dwordx4 v[22:23], v[60:63], off offset:1024
	global_store_dwordx4 v[22:23], v[64:67], off offset:2048
	global_store_dwordx4 v[22:23], v[68:71], off offset:3072
	s_cmp_lg_u32 s101, 0
	s_cbranch_scc1 .Lrp_d_nxb1
	global_store_dwordx2 v[24:25], v[112:113], off
	global_store_dwordx2 v[24:25], v[114:115], off offset:512
	global_store_dwordx2 v[24:25], v[116:117], off offset:1024
	global_store_dwordx2 v[24:25], v[118:119], off offset:1536
.Lrp_d_nxb1:
	v_lshl_add_u64 v[22:23], s[0:1], 1, v[22:23]
	v_lshl_add_u64 v[24:25], s[0:1], 0, v[24:25]
	global_store_dwordx4 v[22:23], v[72:75], off
	global_store_dwordx4 v[22:23], v[76:79], off offset:1024
	global_store_dwordx4 v[22:23], v[80:83], off offset:2048
	global_store_dwordx4 v[22:23], v[84:87], off offset:3072
	s_cmp_lg_u32 s101, 0
	s_cbranch_scc1 .Lrp_d_nxb2
	global_store_dwordx2 v[24:25], v[120:121], off
	global_store_dwordx2 v[24:25], v[122:123], off offset:512
	global_store_dwordx2 v[24:25], v[124:125], off offset:1024
	global_store_dwordx2 v[24:25], v[126:127], off offset:1536
; DI void gemm_rownorm_residual(const Ctx& c, int m0, const bf16* A, int lda, int K, const bf16* Wt, const float* gpost,
;                               const float* xres, float* xdst, bf16* xbdst, bf16* lds, float* rowss, float* rstd_next) {
;     ...
;     ss2 += __shfl_xor(ss2, 1); ss2 += __shfl_xor(ss2, 2);
;     if (part == 0) rstd_next[row] = rsqrtf(ss2 * (1.0f / 1024.0f) + EPS);
.Lrp_d_nxb2:
	v_lshl_add_u64 v[22:23], s[0:1], 1, v[22:23]
	v_lshl_add_u64 v[24:25], s[0:1], 0, v[24:25]
	global_store_dwordx4 v[22:23], v[88:91], off
	global_store_dwordx4 v[22:23], v[92:95], off offset:1024
	global_store_dwordx4 v[22:23], v[96:99], off offset:2048
	global_store_dwordx4 v[22:23], v[100:103], off offset:3072
	s_cmp_lg_u32 s101, 0
	s_cbranch_scc1 .Lrp_d_nxb3
	global_store_dwordx2 v[24:25], v[128:129], off
	global_store_dwordx2 v[24:25], v[130:131], off offset:512
	global_store_dwordx2 v[24:25], v[132:133], off offset:1024
	global_store_dwordx2 v[24:25], v[134:135], off offset:1536
.Lrp_d_nxb3:
	v_lshl_add_u64 v[22:23], s[0:1], 1, v[22:23]
	v_lshl_add_u64 v[24:25], s[0:1], 0, v[24:25]
	ds_swizzle_b32 v136, v36 offset:0x041F
	ds_swizzle_b32 v137, v37 offset:0x041F
	ds_swizzle_b32 v138, v38 offset:0x041F
	ds_swizzle_b32 v139, v39 offset:0x041F
	s_waitcnt lgkmcnt(0)
	v_add_f32_e32 v36, v36, v136
	v_add_f32_e32 v37, v37, v137
	v_add_f32_e32 v38, v38, v138
	v_add_f32_e32 v39, v39, v139
	ds_swizzle_b32 v136, v36 offset:0x081F
	ds_swizzle_b32 v137, v37 offset:0x081F
	ds_swizzle_b32 v138, v38 offset:0x081F
	ds_swizzle_b32 v139, v39 offset:0x081F
	s_waitcnt lgkmcnt(0)
	v_add_f32_e32 v36, v36, v136
	v_add_f32_e32 v37, v37, v137
	v_add_f32_e32 v38, v38, v138
	v_add_f32_e32 v39, v39, v139
	ds_swizzle_b32 v136, v36 offset:0x101F
	ds_swizzle_b32 v137, v37 offset:0x101F
	ds_swizzle_b32 v138, v38 offset:0x101F
	ds_swizzle_b32 v139, v39 offset:0x101F
	s_waitcnt lgkmcnt(0)
	v_add_f32_e32 v36, v36, v136
	v_add_f32_e32 v37, v37, v137
	v_add_f32_e32 v38, v38, v138
	v_add_f32_e32 v39, v39, v139
	ds_swizzle_b32 v136, v36 offset:0x201F
	ds_swizzle_b32 v137, v37 offset:0x201F
	ds_swizzle_b32 v138, v38 offset:0x201F
	ds_swizzle_b32 v139, v39 offset:0x201F
	s_waitcnt lgkmcnt(0)
	v_add_f32_e32 v36, v36, v136
	v_add_f32_e32 v37, v37, v137
	v_add_f32_e32 v38, v38, v138
	v_add_f32_e32 v39, v39, v139
	ds_swizzle_b32 v136, v36 offset:0x401F
	ds_swizzle_b32 v137, v37 offset:0x401F
	ds_swizzle_b32 v138, v38 offset:0x401F
	ds_swizzle_b32 v139, v39 offset:0x401F
	s_waitcnt lgkmcnt(0)
	v_add_f32_e32 v36, v36, v136
	v_add_f32_e32 v37, v37, v137
	v_add_f32_e32 v38, v38, v138
	v_add_f32_e32 v39, v39, v139
	ds_bpermute_b32 v136, v27, v36
	ds_bpermute_b32 v137, v27, v37
	ds_bpermute_b32 v138, v27, v38
	ds_bpermute_b32 v139, v27, v39
	s_waitcnt lgkmcnt(0)
	v_add_f32_e32 v36, v36, v136
	v_add_f32_e32 v37, v37, v137
	v_add_f32_e32 v38, v38, v138
	v_add_f32_e32 v39, v39, v139
	v_fmamk_f32 v36, v36, 0x3a800000, v187
	v_fmamk_f32 v37, v37, 0x3a800000, v187
	v_fmamk_f32 v38, v38, 0x3a800000, v187
	v_fmamk_f32 v39, v39, 0x3a800000, v187
	v_rsq_f32_e32 v36, v36
	v_rsq_f32_e32 v37, v37
	v_rsq_f32_e32 v38, v38
	v_rsq_f32_e32 v39, v39
	s_mov_b64 vcc, exec
	s_mov_b64 exec, 1
	ds_write_b32 v28, v36
	ds_write_b32 v29, v37
	ds_write_b32 v30, v38
	ds_write_b32 v31, v39
	s_mov_b64 exec, vcc
	v_add_u32_e32 v26, 16, v26
	s_add_i32 s100, s100, 1
	s_cmp_eq_u32 s100, 4
	s_cbranch_scc1 .Lrp_d_done
	global_load_dwordx4 v[40:43], v[20:21], off
	global_load_dwordx4 v[44:47], v[20:21], off offset:1024
	global_load_dwordx4 v[48:51], v[20:21], off offset:2048
	global_load_dwordx4 v[52:55], v[20:21], off offset:3072
	global_load_dwordx2 v[104:105], v[18:19], off
	global_load_dwordx2 v[106:107], v[18:19], off offset:512
	global_load_dwordx2 v[108:109], v[18:19], off offset:1024
	global_load_dwordx2 v[110:111], v[18:19], off offset:1536
	v_lshl_add_u64 v[20:21], s[0:1], 1, v[20:21]
	v_lshl_add_u64 v[18:19], s[0:1], 0, v[18:19]
	global_load_dwordx4 v[56:59], v[20:21], off
	global_load_dwordx4 v[60:63], v[20:21], off offset:1024
	global_load_dwordx4 v[64:67], v[20:21], off offset:2048
	global_load_dwordx4 v[68:71], v[20:21], off offset:3072
	global_load_dwordx2 v[112:113], v[18:19], off
	global_load_dwordx2 v[114:115], v[18:19], off offset:512
	global_load_dwordx2 v[116:117], v[18:19], off offset:1024
	global_load_dwordx2 v[118:119], v[18:19], off offset:1536
	v_lshl_add_u64 v[20:21], s[0:1], 1, v[20:21]
	v_lshl_add_u64 v[18:19], s[0:1], 0, v[18:19]
	global_load_dwordx4 v[72:75], v[20:21], off
	global_load_dwordx4 v[76:79], v[20:21], off offset:1024
	global_load_dwordx4 v[80:83], v[20:21], off offset:2048
	global_load_dwordx4 v[84:87], v[20:21], off offset:3072
	global_load_dwordx2 v[120:121], v[18:19], off
	global_load_dwordx2 v[122:123], v[18:19], off offset:512
	global_load_dwordx2 v[124:125], v[18:19], off offset:1024
	global_load_dwordx2 v[126:127], v[18:19], off offset:1536
	v_lshl_add_u64 v[20:21], s[0:1], 1, v[20:21]
	v_lshl_add_u64 v[18:19], s[0:1], 0, v[18:19]
	global_load_dwordx4 v[88:91], v[20:21], off
	global_load_dwordx4 v[92:95], v[20:21], off offset:1024
	global_load_dwordx4 v[96:99], v[20:21], off offset:2048
	global_load_dwordx4 v[100:103], v[20:21], off offset:3072
	global_load_dwordx2 v[128:129], v[18:19], off
	global_load_dwordx2 v[130:131], v[18:19], off offset:512
	global_load_dwordx2 v[132:133], v[18:19], off offset:1024
	global_load_dwordx2 v[134:135], v[18:19], off offset:1536
	v_lshl_add_u64 v[20:21], s[0:1], 1, v[20:21]
	v_lshl_add_u64 v[18:19], s[0:1], 0, v[18:19]
	s_branch .Lrp_d_loop
